# group-local 4-WG barriers only (PA->PB, PE->PF, PF->PA with row remap)
# speedup vs baseline: 1.0003x; 1.0003x over previous
_Z9hymba_fwd4Args:
	s_mov_b32 s100, 0
	s_mov_b32 s101, 0
	s_mov_b32 s12, s2
	s_add_u32 s2, s0, 0xf8
	s_addc_u32 s3, s1, 0
	s_load_dword s13, s[0:1], 0xf8
	v_writelane_b32 v255, s2, 0
	s_nop 1
	v_writelane_b32 v255, s3, 1
	v_readfirstlane_b32 s2, v0
	v_mbcnt_lo_u32_b32 v0, -1, 0
	s_andn2_b32 s2, s2, 63
	v_mbcnt_hi_u32_b32 v0, -1, v0
	v_add_u32_e32 v220, s2, v0
	v_mov_b32_e32 v1, v220
	s_movk_i32 s2, 0x400
	s_nop 0
	v_cmp_gt_i32_e32 vcc, s2, v1
	s_and_saveexec_b64 s[2:3], vcc
	s_cbranch_execz .LBB0_3
	v_add_u32_e32 v0, 0xfffffe00, v1
	v_lshl_add_u32 v1, v1, 2, 0
	v_add_u32_e32 v1, 0x23000, v1
	s_mov_b64 s[4:5], 0
	v_mov_b32_e32 v2, 0
	s_movk_i32 s6, 0x1ff

.LBB0_3:
	s_or_b64 exec, exec, s[2:3]
	s_mov_b64 s[2:3], s[0:1]
	s_waitcnt lgkmcnt(0)
	s_mov_b32 s4, s13
	s_mov_b32 s5, s12
	s_barrier
	s_load_dwordx4 s[4:7], s[2:3], 0xe8
	s_mov_b32 s33, 0
	s_waitcnt lgkmcnt(0)
	s_add_u32 s20, s4, 0x4000
	s_addc_u32 s21, s5, 0
	s_getreg_b32 s32, hwreg(HW_REG_XCC_ID, 0, 4)
	s_add_i32 s32, s32, 1
	s_add_u32 s8, s4, 0x20000
	s_addc_u32 s9, s5, 0
	v_mov_b32_e32 v0, s32
	s_lshl_b32 s32, s12, 2
	v_mov_b32_e32 v1, s32
	s_nop 0
	global_store_dword v1, v0, s[8:9]
	v_writelane_b32 v255, s4, 2
	s_sub_i32 s2, s7, s6
	s_cmp_gt_i32 s2, 1
	v_writelane_b32 v255, s5, 3
	v_writelane_b32 v255, s6, 4
	v_writelane_b32 v255, s7, 5
	s_mov_b32 s2, 0
	v_writelane_b32 v255, s2, 6
	s_cbranch_scc0 .LBB0_8
	v_mov_b32_e32 v0, v220
	s_getreg_b32 s2, hwreg(HW_REG_XCC_ID, 0, 4)
	s_and_b32 s33, s2, 15
	v_cmp_eq_u32_e32 vcc, 0, v0
	s_and_saveexec_b64 s[2:3], vcc
	s_cbranch_execz .LBB0_7
	s_mov_b64 s[4:5], exec
	v_mbcnt_lo_u32_b32 v0, s4, 0
	v_mbcnt_hi_u32_b32 v0, s5, v0
	v_cmp_eq_u32_e32 vcc, 0, v0
	s_and_b64 s[6:7], exec, vcc
	s_mov_b64 exec, s[6:7]
	s_cbranch_execz .LBB0_7
	s_lshl_b32 s6, s33, 8
	s_bcnt1_i32_b64 s4, s[4:5]
	v_mov_b32_e32 v0, s6
	v_mov_b32_e32 v1, s4
	global_atomic_add v0, v1, s[20:21] offset:1024

.LBB0_268:
	s_cmpk_lg_i32 s13, 0x100
	s_cbranch_scc1 .Lxcc_done
	v_readlane_b32 s8, v255, 2
	v_readlane_b32 s9, v255, 3
	s_add_u32 s8, s8, 0x20000
	s_addc_u32 s9, s9, 0
	s_and_b32 s2, s12, 63
	s_lshl_b32 s2, s2, 2
	v_mov_b32_e32 v0, s2
	s_nop 0
	global_load_dword v1, v0, s[8:9] sc1
	global_load_dword v44, v0, s[8:9] offset:256 sc1
	global_load_dword v45, v0, s[8:9] offset:512 sc1
	global_load_dword v46, v0, s[8:9] offset:768 sc1
	s_waitcnt vmcnt(0)
	v_readfirstlane_b32 s2, v1
	v_readfirstlane_b32 s3, v44
	v_readfirstlane_b32 s4, v45
	v_readfirstlane_b32 s5, v46
	s_cmp_eq_u32 s2, 0
	s_cbranch_scc1 .Lxcc_done
	s_cmp_lg_u32 s2, s3
	s_cbranch_scc1 .Lxcc_done
	s_cmp_lg_u32 s2, s4
	s_cbranch_scc1 .Lxcc_done
	s_cmp_lg_u32 s2, s5
	s_cbranch_scc1 .Lxcc_done
	s_mov_b32 s101, 1

.LBB0_272:
	v_readlane_b32 s8, v255, 2
	s_mul_i32 s15, s92, 6
	v_readlane_b32 s10, v255, 4
	v_readlane_b32 s11, v255, 5
	s_or_b32 s4, s15, 1
	s_mov_b64 s[6:7], s[10:11]
	s_cmp_le_i32 s6, s4
	s_cselect_b64 s[2:3], -1, 0
	s_cmp_lt_i32 s4, s7
	s_cselect_b64 s[4:5], -1, 0
	s_and_b64 s[2:3], s[2:3], s[4:5]
	s_bitcmp0_b32 s92, 0
	s_cselect_b64 s[4:5], -1, 0
	v_readlane_b32 s9, v255, 3
	v_writelane_b32 v255, s4, 55
	s_add_i32 s30, s15, 2
	s_cmp_lt_i32 s30, s7
	v_writelane_b32 v255, s5, 56
	v_writelane_b32 v255, s15, 57
	s_cselect_b64 s[6:7], -1, 0
	s_and_b64 vcc, exec, s[2:3]
	s_cbranch_vccz .LBB0_354
	s_mov_b64 s[8:9], s[0:1]
	s_mov_b32 s31, s13
	s_mov_b32 s34, s12
	s_cmpk_lg_i32 s13, 0x100
	s_cbranch_scc1 .Lpa_noremap
	s_and_b32 s34, s12, 7
	s_lshl_b32 s34, s34, 5
	s_bfe_u32 s2, s12, 0x30003
	s_lshl_b32 s2, s2, 2
	s_or_b32 s34, s34, s2
	s_lshr_b32 s2, s12, 6
	s_or_b32 s34, s34, s2
.Lpa_noremap:
	v_mov_b32_e32 v148, v220
	s_cmpk_gt_i32 s34, 0xff
	v_readfirstlane_b32 s4, v148
	s_cbranch_scc1 .LBB0_305
	v_readlane_b32 s24, v255, 55
	v_readlane_b32 s25, v255, 56
	s_and_b64 s[2:3], s[24:25], exec
	s_mov_b32 s2, 0x60600000
	s_cselect_b32 s5, s2, 0x6a600000
	s_cselect_b32 s15, 0x6a600000, s2
	s_cmp_gt_u32 s92, 1
	s_cselect_b64 s[18:19], -1, 0
	s_cmp_lg_u32 s92, 0
	s_load_dwordx2 s[10:11], s[8:9], 0xe8
	s_load_dwordx2 s[22:23], s[8:9], 0x50
	s_cselect_b64 s[20:21], -1, 0
	s_and_b64 s[2:3], s[24:25], exec
	s_mov_b32 s2, 0x72600000
	s_cselect_b32 s16, s2, 0x58600000
	s_ashr_i32 s4, s4, 3
	s_and_b32 s24, s4, -8
	s_waitcnt lgkmcnt(0)
	s_add_u32 s35, s10, s5
	s_addc_u32 s48, s11, 0
	v_and_b32_e32 v0, 63, v148
	s_add_u32 s4, s10, s15
	v_lshlrev_b32_e32 v150, 5, v0
	v_lshlrev_b32_e32 v176, 4, v0
	s_addc_u32 s5, s11, 0
	v_lshlrev_b32_e32 v0, 2, v0
	s_add_u32 s49, s10, s16
	v_xor_b32_e32 v208, 4, v0
	v_xor_b32_e32 v209, 8, v0
	v_xor_b32_e32 v210, 16, v0
	v_xor_b32_e32 v211, 32, v0
	v_xor_b32_e32 v212, 64, v0
	v_xor_b32_e32 v213, 0x80, v0
	v_lshl_add_u64 v[154:155], s[4:5], 0, v[176:177]
	v_lshl_add_u64 v[0:1], s[10:11], 0, v[176:177]
	s_mov_b64 s[4:5], 0x26600000
	s_addc_u32 s50, s11, 0
	v_lshl_add_u64 v[156:157], v[0:1], 0, s[4:5]
	v_readlane_b32 s4, v255, 53
	v_ashrrev_i32_e32 v149, 31, v148
	v_readlane_b32 s5, v255, 54
	s_add_u32 s4, s10, s4
	v_lshlrev_b64 v[0:1], 4, v[148:149]
	s_addc_u32 s5, s11, s5
	v_lshl_add_u64 v[158:159], s[4:5], 0, v[0:1]
	v_readlane_b32 s4, v255, 51
	v_readlane_b32 s5, v255, 52
	s_add_u32 s4, s22, s4
	s_addc_u32 s5, s23, s5
	s_movk_i32 s2, 0x400
	v_lshl_add_u64 v[160:161], s[4:5], 0, v[0:1]
	s_lshl_b32 s4, s34, 6
	v_cmp_gt_i32_e64 s[2:3], s2, v148
	v_mov_b32_e32 v151, v177
	v_or_b32_e32 v152, 0x1000, v176
	v_mov_b32_e32 v153, v177
	v_add_u32_e32 v214, 0, v176
	v_lshlrev_b32_e32 v149, 6, v148
	s_add_i32 s51, s4, s24
	s_lshl_b32 s56, s31, 6
	v_cndmask_b32_e64 v215, 0, 1, s[18:19]
	s_branch .LBB0_276

.LBB0_305:
	s_andn2_b64 vcc, exec, s[6:7]
	s_barrier
	s_cbranch_vccnz .LBB0_354
	s_cmpk_lg_i32 s13, 0x100
	s_cbranch_scc1 .Lgb0_orig
	s_waitcnt vmcnt(0)
	s_barrier
	s_add_u32 s100, s100, 4
	v_readfirstlane_b32 s2, v220
	s_lshr_b32 s2, s2, 6
	s_cmp_lg_u32 s2, 0
	s_cbranch_scc1 .Lgb0_wait
	v_readlane_b32 s8, v255, 2
	v_readlane_b32 s9, v255, 3
	s_add_u32 s8, s8, 0x21000
	s_addc_u32 s9, s9, 0
	s_and_b32 s2, s12, 63
	s_lshl_b32 s2, s2, 7
	s_add_u32 s8, s8, s2
	s_addc_u32 s9, s9, 0
	s_cmp_eq_u32 s101, 1
	s_cbranch_scc1 .Lgb0_norel
	buffer_wbl2 sc1
	s_waitcnt vmcnt(0)
.Lgb0_norel:
	v_mov_b32_e32 v0, 0
	v_mov_b32_e32 v1, 1
	s_mov_b64 s[26:27], exec
	s_mov_b64 exec, 1
	s_mov_b32 s3, 0
	global_atomic_add v0, v1, s[8:9]
.Lgb0_poll:
	global_load_dword v1, v0, s[8:9] sc1
	s_waitcnt vmcnt(0)
	v_readfirstlane_b32 s2, v1
	s_cmp_ge_u32 s2, s100
	s_cbranch_scc1 .Lgb0_done
	s_add_u32 s3, s3, 1
	s_cmp_gt_u32 s3, 0x10000
	s_cbranch_scc1 .Lgb0_done
	s_sleep 1
	s_branch .Lgb0_poll
.Lgb0_done:
	buffer_inv sc1
	s_waitcnt vmcnt(0)
	s_mov_b64 exec, s[26:27]
.Lgb0_wait:
	s_barrier
	s_branch .LBB0_354
.Lgb0_orig:
	s_waitcnt vmcnt(0)
	v_mov_b32_e32 v0, v220
	s_barrier
	s_nop 0
	v_cmp_eq_u32_e32 vcc, 0, v0
	s_and_saveexec_b64 s[2:3], vcc
	s_cbranch_execz .LBB0_353
	v_readlane_b32 s4, v255, 6
	s_waitcnt vmcnt(0) expcnt(0) lgkmcnt(0)
	s_nop 0
	v_mov_b32_e32 v0, s4
	ds_read_b32 v2, v0
	ds_read_b32 v0, v0 offset:4
	s_waitcnt lgkmcnt(1)
	v_cmp_ne_u32_e32 vcc, 0, v2
	s_cbranch_vccnz .LBB0_321
	v_readlane_b32 s8, v255, 0
	v_readlane_b32 s9, v255, 1
	s_load_dwordx2 s[4:5], s[8:9], 0x4
	s_mov_b32 s15, 0
	s_waitcnt lgkmcnt(0)
	s_mul_i32 s11, s4, s13
	s_mul_i32 s11, s11, s5
	s_branch .LBB0_310

.LBB0_854:
	s_andn2_b64 vcc, exec, s[4:5]
	s_cbranch_vccnz .LBB0_903
	s_cmpk_lg_i32 s13, 0x100
	s_cbranch_scc1 .Lgb1_orig
	s_waitcnt vmcnt(0)
	s_barrier
	s_add_u32 s100, s100, 4
	v_readfirstlane_b32 s2, v220
	s_lshr_b32 s2, s2, 6
	s_cmp_lg_u32 s2, 0
	s_cbranch_scc1 .Lgb1_wait
	v_readlane_b32 s8, v255, 2
	v_readlane_b32 s9, v255, 3
	s_add_u32 s8, s8, 0x21000
	s_addc_u32 s9, s9, 0
	s_and_b32 s2, s12, 63
	s_lshl_b32 s2, s2, 7
	s_add_u32 s8, s8, s2
	s_addc_u32 s9, s9, 0
	s_cmp_eq_u32 s101, 1
	s_cbranch_scc1 .Lgb1_norel
	buffer_wbl2 sc1
	s_waitcnt vmcnt(0)

.Lgb1_orig:
	s_waitcnt vmcnt(0)
	v_mov_b32_e32 v0, v220
	s_waitcnt vmcnt(0)
	s_barrier
	s_nop 0
	v_cmp_eq_u32_e32 vcc, 0, v0
	s_and_saveexec_b64 s[2:3], vcc
	s_cbranch_execz .LBB0_902
	v_readlane_b32 s6, v255, 6
	s_waitcnt vmcnt(0) expcnt(0) lgkmcnt(0)
	s_nop 0
	v_mov_b32_e32 v0, s6
	ds_read_b32 v2, v0
	ds_read_b32 v0, v0 offset:4
	s_waitcnt lgkmcnt(1)
	v_cmp_ne_u32_e32 vcc, 0, v2
	s_cbranch_vccnz .LBB0_870
	v_readlane_b32 s8, v255, 0
	v_readlane_b32 s9, v255, 1
	s_load_dwordx2 s[6:7], s[8:9], 0x4
	s_mov_b32 s16, 0
	s_waitcnt lgkmcnt(0)
	s_mul_i32 s15, s6, s13
	s_mul_i32 s15, s15, s7
	s_branch .LBB0_859

.Lmy_long271:
	s_getpc_b64 s[98:99]

.LBB0_935:
	s_cmpk_lg_i32 s13, 0x100
	s_cbranch_scc1 .Lgb2_orig
	s_waitcnt vmcnt(0)
	s_barrier
	s_add_u32 s100, s100, 4
	v_readfirstlane_b32 s2, v220
	s_lshr_b32 s2, s2, 6
	s_cmp_lg_u32 s2, 0
	s_cbranch_scc1 .Lgb2_wait
	v_readlane_b32 s8, v255, 2
	v_readlane_b32 s9, v255, 3
	s_add_u32 s8, s8, 0x21000
	s_addc_u32 s9, s9, 0
	s_and_b32 s2, s12, 63
	s_lshl_b32 s2, s2, 7
	s_add_u32 s8, s8, s2
	s_addc_u32 s9, s9, 0
	s_cmp_eq_u32 s101, 1
	s_cbranch_scc1 .Lgb2_norel
	buffer_wbl2 sc1
	s_waitcnt vmcnt(0)

.LBB0_981:
	v_readlane_b32 s4, v255, 2
	v_readlane_b32 s6, v255, 4
	v_readlane_b32 s7, v255, 5
	s_cmp_lt_i32 s6, 26
	v_readlane_b32 s5, v255, 3
	s_cselect_b64 s[2:3], -1, 0
	s_cmp_gt_i32 s7, 25
	s_cselect_b64 s[4:5], -1, 0
	s_and_b64 s[2:3], s[2:3], s[4:5]
	s_and_b64 vcc, exec, s[2:3]
	s_cbranch_vccz .LBB0_987
	s_cmpk_lg_i32 s13, 0x100
	s_cbranch_scc1 .Lfn_noremap
	s_and_b32 s2, s12, 7
	s_lshl_b32 s2, s2, 5
	s_bfe_u32 s3, s12, 0x30003
	s_lshl_b32 s3, s3, 2
	s_or_b32 s2, s2, s3
	s_lshr_b32 s3, s12, 6
	s_or_b32 s12, s2, s3
.Lfn_noremap:
	s_lshl_b32 s3, s12, 3
	v_readfirstlane_b32 s2, v220
	s_ashr_i32 s2, s2, 6
	s_add_i32 s14, s2, s3
	s_cmpk_gt_i32 s14, 0x7ff
	s_cbranch_scc1 .LBB0_987
	s_load_dwordx2 s[8:9], s[0:1], 0xd8
	s_load_dwordx4 s[4:7], s[0:1], 0xe0
	v_and_b32_e32 v64, 63, v220
	v_lshlrev_b32_e32 v128, 5, v64
	v_or_b32_e32 v130, 0x1000, v128
	v_or_b32_e32 v132, 0x2000, v128
	v_or_b32_e32 v134, 0x3000, v128
	s_waitcnt lgkmcnt(0)
	global_load_dwordx4 v[0:3], v128, s[8:9] offset:16
	global_load_dwordx4 v[4:7], v128, s[8:9]
	global_load_dwordx4 v[8:11], v128, s[8:9] offset:2064
	global_load_dwordx4 v[12:15], v128, s[8:9] offset:2048
	global_load_dwordx4 v[16:19], v130, s[8:9] offset:16
	global_load_dwordx4 v[20:23], v130, s[8:9]
	global_load_dwordx4 v[24:27], v130, s[8:9] offset:2064
	global_load_dwordx4 v[28:31], v130, s[8:9] offset:2048
	global_load_dwordx4 v[32:35], v132, s[8:9] offset:16
	global_load_dwordx4 v[36:39], v132, s[8:9]
	global_load_dwordx4 v[40:43], v132, s[8:9] offset:2064
	global_load_dwordx4 v[44:47], v132, s[8:9] offset:2048
	global_load_dwordx4 v[48:51], v134, s[8:9] offset:16
	global_load_dwordx4 v[52:55], v134, s[8:9]
	global_load_dwordx4 v[56:59], v134, s[8:9] offset:2064
	global_load_dwordx4 v[60:63], v134, s[8:9] offset:2048
	s_lshl_b32 s15, s13, 3
	s_add_u32 s16, s6, 0x6a600000
	s_addc_u32 s17, s7, 0
	s_add_u32 s18, s6, 0x72600000
	v_mov_b32_e32 v129, 0
	v_lshlrev_b32_e32 v136, 4, v64
	s_addc_u32 s19, s7, 0
	v_lshlrev_b32_e32 v64, 2, v64
	s_lshl_b32 s0, s12, 6
	s_lshl_b32 s1, s2, 3
	v_xor_b32_e32 v170, 4, v64
	v_xor_b32_e32 v171, 8, v64
	v_xor_b32_e32 v172, 16, v64
	v_xor_b32_e32 v173, 32, v64
	v_xor_b32_e32 v174, 64, v64
	v_xor_b32_e32 v175, 0x80, v64
	v_mov_b32_e32 v137, v129
	s_add_i32 s2, s0, s1
	v_lshl_add_u64 v[64:65], s[4:5], 0, v[128:129]
	s_mov_b64 s[0:1], 0x3810
	v_mov_b32_e32 v131, v129
	v_mov_b32_e32 v133, v129
	v_mov_b32_e32 v135, v129
	v_or_b32_e32 v138, 0x1000, v136
	v_mov_b32_e32 v139, v129
	s_or_b32 s20, s2, 1
	s_lshl_b32 s21, s13, 6
	v_lshl_add_u64 v[140:141], v[64:65], 0, s[0:1]
	v_lshl_add_u64 v[142:143], s[6:7], 0, v[136:137]
	s_mov_b32 s22, 0x6a601000
	s_mov_b32 s23, 0x72601000
	v_mov_b32_e32 v176, 0x358637bd
	s_mov_b32 s24, 0x800000
	s_movk_i32 s25, 0xd000
	s_movk_i32 s26, 0xe000
	s_movk_i32 s27, 0xf000
	s_mov_b64 s[6:7], 0x8000

	.amdhsa_kernel _Z9hymba_fwd4Args
		.amdhsa_group_segment_fixed_size 0
		.amdhsa_private_segment_fixed_size 0
		.amdhsa_kernarg_size 504
		.amdhsa_user_sgpr_count 2
		.amdhsa_user_sgpr_dispatch_ptr 0
		.amdhsa_user_sgpr_queue_ptr 0
		.amdhsa_user_sgpr_kernarg_segment_ptr 1
		.amdhsa_user_sgpr_dispatch_id 0
		.amdhsa_user_sgpr_kernarg_preload_length 0
		.amdhsa_user_sgpr_kernarg_preload_offset 0
		.amdhsa_user_sgpr_private_segment_size 0
		.amdhsa_uses_dynamic_stack 0
		.amdhsa_enable_private_segment 0
		.amdhsa_system_sgpr_workgroup_id_x 1
		.amdhsa_system_sgpr_workgroup_id_y 0
		.amdhsa_system_sgpr_workgroup_id_z 0
		.amdhsa_system_sgpr_workgroup_info 0
		.amdhsa_system_vgpr_workitem_id 0
		.amdhsa_next_free_vgpr 256
		.amdhsa_next_free_sgpr 102
		.amdhsa_accum_offset 256
		.amdhsa_reserve_vcc 1
		.amdhsa_float_round_mode_32 0
		.amdhsa_float_round_mode_16_64 0
		.amdhsa_float_denorm_mode_32 3
		.amdhsa_float_denorm_mode_16_64 3
		.amdhsa_dx10_clamp 1
		.amdhsa_ieee_mode 1
		.amdhsa_fp16_overflow 0
		.amdhsa_tg_split 0
		.amdhsa_exception_fp_ieee_invalid_op 0
		.amdhsa_exception_fp_denorm_src 0
		.amdhsa_exception_fp_ieee_div_zero 0
		.amdhsa_exception_fp_ieee_overflow 0
		.amdhsa_exception_fp_ieee_underflow 0
		.amdhsa_exception_fp_ieee_inexact 0
		.amdhsa_exception_int_div_zero 0
	.end_amdhsa_kernel

amdhsa.kernels:
  - .agpr_count:     0
    .args:
      - .offset:         0
        .size:           248
        .value_kind:     by_value
      - .offset:         248
        .size:           4
        .value_kind:     hidden_block_count_x
      - .offset:         252
        .size:           4
        .value_kind:     hidden_block_count_y
      - .offset:         256
        .size:           4
        .value_kind:     hidden_block_count_z
      - .offset:         260
        .size:           2
        .value_kind:     hidden_group_size_x
      - .offset:         262
        .size:           2
        .value_kind:     hidden_group_size_y
      - .offset:         264
        .size:           2
        .value_kind:     hidden_group_size_z
      - .offset:         266
        .size:           2
        .value_kind:     hidden_remainder_x
      - .offset:         268
        .size:           2
        .value_kind:     hidden_remainder_y
      - .offset:         270
        .size:           2
        .value_kind:     hidden_remainder_z
      - .offset:         288
        .size:           8
        .value_kind:     hidden_global_offset_x
      - .offset:         296
        .size:           8
        .value_kind:     hidden_global_offset_y
      - .offset:         304
        .size:           8
        .value_kind:     hidden_global_offset_z
      - .offset:         312
        .size:           2
        .value_kind:     hidden_grid_dims
      - .offset:         368
        .size:           4
        .value_kind:     hidden_dynamic_lds_size
    .group_segment_fixed_size: 0
    .kernarg_segment_align: 8
    .kernarg_segment_size: 504
    .language:       OpenCL C
    .language_version:
      - 2
      - 0
    .max_flat_workgroup_size: 512
    .name:           _Z9hymba_fwd4Args
    .private_segment_fixed_size: 0
    .sgpr_count:     108
    .sgpr_spill_count: 64
    .symbol:         _Z9hymba_fwd4Args.kd
    .uniform_work_group_size: 1
    .uses_dynamic_stack: false
    .vgpr_count:     256
    .vgpr_spill_count: 0
    .wavefront_size: 64
